# spin-loop tightening: s_sleep removed from the barrier poll loops (on combined+final version)
# speedup vs baseline: 1.0027x; 1.0027x over previous
; __device__ __forceinline__ unsigned xb_ld(unsigned* p)              { return __hip_atomic_load(p, __ATOMIC_RELAXED, __HIP_MEMORY_SCOPE_AGENT); }
; __device__ __forceinline__ void xcd_barrier_complete(unsigned* bar, unsigned x, unsigned& nloc, unsigned& nx) {
;     ...
;     for (;;) {
;         sum = 0u; cnt = 0u; mine = 0u;
; #pragma unroll
;         for (unsigned j = 0; j < 16; ++j) { const unsigned c = xb_ld(&bar[XB_XCNT(j)]); sum += c; cnt += (c > 0u) ? 1u : 0u; mine = (j == x) ? c : mine; }
;         if (sum == G) break;
;         __builtin_amdgcn_s_sleep(1);
;         if ((++sp & 255u) == 0u) { if (xb_ld(&bar[XB_TMO])) break; if (sp > XB_SPIN_CAP) { atomicAdd(&bar[XB_TMO], 1u); break; } }
;     }
.LBB0_57:
	global_load_dword v16, v17, s[14:15] sc1
	global_load_dword v1, v17, s[16:17] sc1
	global_load_dword v2, v17, s[18:19] sc1
	global_load_dword v3, v17, s[20:21] sc1
	global_load_dword v4, v17, s[22:23] sc1
	global_load_dword v5, v17, s[24:25] sc1
	global_load_dword v6, v17, s[26:27] sc1
	global_load_dword v7, v17, s[28:29] sc1
	global_load_dword v8, v17, s[30:31] sc1
	global_load_dword v9, v17, s[34:35] sc1
	global_load_dword v10, v17, s[36:37] sc1
	global_load_dword v11, v17, s[40:41] sc1
	global_load_dword v12, v17, s[42:43] sc1
	global_load_dword v13, v17, s[44:45] sc1
	global_load_dword v14, v17, s[46:47] sc1
	global_load_dword v15, v17, s[48:49] sc1
	s_mov_b64 s[50:51], -1
	s_mov_b64 s[52:53], -1
	s_waitcnt vmcnt(14)
	v_add_u32_e32 v18, v1, v16
	s_waitcnt vmcnt(13)
	v_add_u32_e32 v18, v18, v2
	s_waitcnt vmcnt(12)
	v_add_u32_e32 v18, v18, v3
	s_waitcnt vmcnt(11)
	v_add_u32_e32 v18, v18, v4
	s_waitcnt vmcnt(10)
	v_add_u32_e32 v18, v18, v5
	s_waitcnt vmcnt(9)
	v_add_u32_e32 v18, v18, v6
	s_waitcnt vmcnt(8)
	v_add_u32_e32 v18, v18, v7
	s_waitcnt vmcnt(7)
	v_add_u32_e32 v18, v18, v8
	s_waitcnt vmcnt(6)
	v_add_u32_e32 v18, v18, v9
	s_waitcnt vmcnt(5)
	v_add_u32_e32 v18, v18, v10
	s_waitcnt vmcnt(4)
	v_add_u32_e32 v18, v18, v11
	s_waitcnt vmcnt(3)
	v_add_u32_e32 v18, v18, v12
	s_waitcnt vmcnt(2)
	v_add_u32_e32 v18, v18, v13
	s_waitcnt vmcnt(1)
	v_add_u32_e32 v18, v18, v14
	s_waitcnt vmcnt(0)
	v_add_u32_e32 v18, v18, v15
	v_cmp_eq_u32_e32 vcc, s3, v18
	s_cbranch_vccnz .LBB0_56
	s_and_b32 s50, s13, 0xff
	s_cmp_eq_u32 s50, 0
	s_mov_b64 s[50:51], -1
	s_mov_b64 s[54:55], -1
	s_cbranch_scc1 .LBB0_61
	s_and_b64 vcc, exec, s[54:55]
	s_cbranch_vccz .LBB0_56

; __device__ __forceinline__ unsigned xb_ld(unsigned* p)              { return __hip_atomic_load(p, __ATOMIC_RELAXED, __HIP_MEMORY_SCOPE_AGENT); }
; __device__ __forceinline__ unsigned xb_add(unsigned* p, unsigned v) { return __hip_atomic_fetch_add(p, v, __ATOMIC_RELAXED, __HIP_MEMORY_SCOPE_AGENT); }
; #define XB_SPIN(cond, bar) do { unsigned _sp = 0; while (cond) { __builtin_amdgcn_s_sleep(1); \
;     if ((++_sp & 255u) == 0u) { if (xb_ld(&(bar)[XB_TMO])) break; if (_sp > XB_SPIN_CAP) { atomicAdd(&(bar)[XB_TMO], 1u); break; } } } } while (0)
; __device__ __forceinline__ void xcd_barrier(const XcdBarrier& b) {
;     ...
;             else XB_SPIN(xb_ld(&bar[XB_TOPGEN]) == tg, bar);
;             __builtin_amdgcn_fence(__ATOMIC_ACQUIRE, "agent");
;             xb_add(&bar[XB_XGEN(b.x)], 1u);
;             asm volatile("s_waitcnt vmcnt(0)" ::: "memory");
;         } else {
;             XB_SPIN(xb_ld(&bar[XB_XGEN(b.x)]) == gen, bar);
.LBB0_74:
	s_and_b32 s13, s3, 0xff
	s_mov_b64 s[26:27], -1
	s_cmp_lg_u32 s13, 0
	s_mov_b64 s[30:31], -1
	s_cbranch_scc0 .LBB0_77
	s_and_b64 vcc, exec, s[30:31]
	s_cbranch_vccz .LBB0_73

; __device__ __forceinline__ unsigned xb_ld(unsigned* p)              { return __hip_atomic_load(p, __ATOMIC_RELAXED, __HIP_MEMORY_SCOPE_AGENT); }
; __device__ __forceinline__ unsigned xb_add(unsigned* p, unsigned v) { return __hip_atomic_fetch_add(p, v, __ATOMIC_RELAXED, __HIP_MEMORY_SCOPE_AGENT); }
; #define XB_SPIN(cond, bar) do { unsigned _sp = 0; while (cond) { __builtin_amdgcn_s_sleep(1); \
;     if ((++_sp & 255u) == 0u) { if (xb_ld(&(bar)[XB_TMO])) break; if (_sp > XB_SPIN_CAP) { atomicAdd(&(bar)[XB_TMO], 1u); break; } } } } while (0)
; __device__ __forceinline__ void xcd_barrier(const XcdBarrier& b) {
;     ...
;             else XB_SPIN(xb_ld(&bar[XB_TOPGEN]) == tg, bar);
;             __builtin_amdgcn_fence(__ATOMIC_ACQUIRE, "agent");
;             xb_add(&bar[XB_XGEN(b.x)], 1u);
;             asm volatile("s_waitcnt vmcnt(0)" ::: "memory");
;         } else {
;             XB_SPIN(xb_ld(&bar[XB_XGEN(b.x)]) == gen, bar);
.LBB0_91:
	s_and_b32 s13, s3, 0xff
	s_cmp_lg_u32 s13, 0
	s_mov_b64 s[28:29], -1
	s_cbranch_scc0 .LBB0_94
	s_mov_b64 s[30:31], -1
	s_and_b64 vcc, exec, s[28:29]
	s_cbranch_vccz .LBB0_90

; __device__ __forceinline__ unsigned xb_ld(unsigned* p)              { return __hip_atomic_load(p, __ATOMIC_RELAXED, __HIP_MEMORY_SCOPE_AGENT); }
; __device__ __forceinline__ void xcd_barrier_complete(unsigned* bar, unsigned x, unsigned& nloc, unsigned& nx) {
;     ...
;     for (;;) {
;         sum = 0u; cnt = 0u; mine = 0u;
; #pragma unroll
;         for (unsigned j = 0; j < 16; ++j) { const unsigned c = xb_ld(&bar[XB_XCNT(j)]); sum += c; cnt += (c > 0u) ? 1u : 0u; mine = (j == x) ? c : mine; }
;         if (sum == G) break;
;         __builtin_amdgcn_s_sleep(1);
;         if ((++sp & 255u) == 0u) { if (xb_ld(&bar[XB_TMO])) break; if (sp > XB_SPIN_CAP) { atomicAdd(&bar[XB_TMO], 1u); break; } }
;     }
.LBB0_428:
	global_load_dword v16, v17, s[6:7] sc1
	global_load_dword v1, v17, s[14:15] sc1
	global_load_dword v2, v17, s[16:17] sc1
	global_load_dword v3, v17, s[18:19] sc1
	global_load_dword v4, v17, s[20:21] sc1
	global_load_dword v5, v17, s[22:23] sc1
	global_load_dword v6, v17, s[24:25] sc1
	global_load_dword v7, v17, s[26:27] sc1
	global_load_dword v8, v17, s[28:29] sc1
	global_load_dword v9, v17, s[30:31] sc1
	global_load_dword v10, v17, s[34:35] sc1
	global_load_dword v11, v17, s[36:37] sc1
	global_load_dword v12, v17, s[40:41] sc1
	global_load_dword v13, v17, s[42:43] sc1
	global_load_dword v14, v17, s[44:45] sc1
	global_load_dword v15, v17, s[46:47] sc1
	s_mov_b64 s[48:49], -1
	s_mov_b64 s[50:51], -1
	s_waitcnt vmcnt(14)
	v_add_u32_e32 v18, v1, v16
	s_waitcnt vmcnt(13)
	v_add_u32_e32 v18, v18, v2
	s_waitcnt vmcnt(12)
	v_add_u32_e32 v18, v18, v3
	s_waitcnt vmcnt(11)
	v_add_u32_e32 v18, v18, v4
	s_waitcnt vmcnt(10)
	v_add_u32_e32 v18, v18, v5
	s_waitcnt vmcnt(9)
	v_add_u32_e32 v18, v18, v6
	s_waitcnt vmcnt(8)
	v_add_u32_e32 v18, v18, v7
	s_waitcnt vmcnt(7)
	v_add_u32_e32 v18, v18, v8
	s_waitcnt vmcnt(6)
	v_add_u32_e32 v18, v18, v9
	s_waitcnt vmcnt(5)
	v_add_u32_e32 v18, v18, v10
	s_waitcnt vmcnt(4)
	v_add_u32_e32 v18, v18, v11
	s_waitcnt vmcnt(3)
	v_add_u32_e32 v18, v18, v12
	s_waitcnt vmcnt(2)
	v_add_u32_e32 v18, v18, v13
	s_waitcnt vmcnt(1)
	v_add_u32_e32 v18, v18, v14
	s_waitcnt vmcnt(0)
	v_add_u32_e32 v18, v18, v15
	v_cmp_eq_u32_e32 vcc, s3, v18
	s_cbranch_vccnz .LBB0_427
	s_and_b32 s48, s13, 0xff
	s_cmp_eq_u32 s48, 0
	s_mov_b64 s[48:49], -1
	s_mov_b64 s[52:53], -1
	s_cbranch_scc1 .LBB0_432
	s_and_b64 vcc, exec, s[52:53]
	s_cbranch_vccz .LBB0_426

; __device__ __forceinline__ unsigned xb_ld(unsigned* p)              { return __hip_atomic_load(p, __ATOMIC_RELAXED, __HIP_MEMORY_SCOPE_AGENT); }
; __device__ __forceinline__ unsigned xb_add(unsigned* p, unsigned v) { return __hip_atomic_fetch_add(p, v, __ATOMIC_RELAXED, __HIP_MEMORY_SCOPE_AGENT); }
; #define XB_SPIN(cond, bar) do { unsigned _sp = 0; while (cond) { __builtin_amdgcn_s_sleep(1); \
;     if ((++_sp & 255u) == 0u) { if (xb_ld(&(bar)[XB_TMO])) break; if (_sp > XB_SPIN_CAP) { atomicAdd(&(bar)[XB_TMO], 1u); break; } } } } while (0)
; __device__ __forceinline__ void xcd_barrier(const XcdBarrier& b) {
;     ...
;             else XB_SPIN(xb_ld(&bar[XB_TOPGEN]) == tg, bar);
;             __builtin_amdgcn_fence(__ATOMIC_ACQUIRE, "agent");
;             xb_add(&bar[XB_XGEN(b.x)], 1u);
;             asm volatile("s_waitcnt vmcnt(0)" ::: "memory");
;         } else {
;             XB_SPIN(xb_ld(&bar[XB_XGEN(b.x)]) == gen, bar);
.LBB0_444:
	s_and_b32 s13, s3, 0xff
	s_mov_b64 s[24:25], -1
	s_cmp_lg_u32 s13, 0
	s_mov_b64 s[28:29], -1
	s_cbranch_scc0 .LBB0_447
	s_and_b64 vcc, exec, s[28:29]
	s_cbranch_vccz .LBB0_443

; __device__ __forceinline__ unsigned xb_ld(unsigned* p)              { return __hip_atomic_load(p, __ATOMIC_RELAXED, __HIP_MEMORY_SCOPE_AGENT); }
; __device__ __forceinline__ unsigned xb_add(unsigned* p, unsigned v) { return __hip_atomic_fetch_add(p, v, __ATOMIC_RELAXED, __HIP_MEMORY_SCOPE_AGENT); }
; #define XB_SPIN(cond, bar) do { unsigned _sp = 0; while (cond) { __builtin_amdgcn_s_sleep(1); \
;     if ((++_sp & 255u) == 0u) { if (xb_ld(&(bar)[XB_TMO])) break; if (_sp > XB_SPIN_CAP) { atomicAdd(&(bar)[XB_TMO], 1u); break; } } } } while (0)
; __device__ __forceinline__ void xcd_barrier(const XcdBarrier& b) {
;     ...
;             else XB_SPIN(xb_ld(&bar[XB_TOPGEN]) == tg, bar);
;             __builtin_amdgcn_fence(__ATOMIC_ACQUIRE, "agent");
;             xb_add(&bar[XB_XGEN(b.x)], 1u);
;             asm volatile("s_waitcnt vmcnt(0)" ::: "memory");
;         } else {
;             XB_SPIN(xb_ld(&bar[XB_XGEN(b.x)]) == gen, bar);
.LBB0_461:
	s_and_b32 s13, s3, 0xff
	s_cmp_lg_u32 s13, 0
	s_mov_b64 s[26:27], -1
	s_cbranch_scc0 .LBB0_464
	s_mov_b64 s[28:29], -1
	s_and_b64 vcc, exec, s[26:27]
	s_cbranch_vccz .LBB0_460

; __device__ __forceinline__ unsigned xb_ld(unsigned* p)              { return __hip_atomic_load(p, __ATOMIC_RELAXED, __HIP_MEMORY_SCOPE_AGENT); }
; __device__ __forceinline__ void xcd_barrier_complete(unsigned* bar, unsigned x, unsigned& nloc, unsigned& nx) {
;     ...
;     for (;;) {
;         sum = 0u; cnt = 0u; mine = 0u;
; #pragma unroll
;         for (unsigned j = 0; j < 16; ++j) { const unsigned c = xb_ld(&bar[XB_XCNT(j)]); sum += c; cnt += (c > 0u) ? 1u : 0u; mine = (j == x) ? c : mine; }
;         if (sum == G) break;
;         __builtin_amdgcn_s_sleep(1);
;         if ((++sp & 255u) == 0u) { if (xb_ld(&bar[XB_TMO])) break; if (sp > XB_SPIN_CAP) { atomicAdd(&bar[XB_TMO], 1u); break; } }
;     }
.LBB0_541:
	v_readlane_b32 s4, v246, 48
	v_readlane_b32 s5, v246, 49
	s_mov_b64 s[6:7], -1
	s_nop 3
	global_load_dword v2, v3, s[4:5] sc1
	v_readlane_b32 s4, v246, 50
	v_readlane_b32 s5, v246, 51
	s_nop 4
	global_load_dword v4, v3, s[4:5] sc1
	v_readlane_b32 s4, v246, 52
	v_readlane_b32 s5, v246, 53
	s_waitcnt vmcnt(0)
	v_add_u32_e32 v19, v4, v2
	s_nop 2
	global_load_dword v5, v3, s[4:5] sc1
	v_readlane_b32 s4, v246, 54
	v_readlane_b32 s5, v246, 55
	s_waitcnt vmcnt(0)
	v_add_u32_e32 v19, v19, v5
	s_nop 2
	global_load_dword v6, v3, s[4:5] sc1
	v_readlane_b32 s4, v246, 56
	v_readlane_b32 s5, v246, 57
	s_waitcnt vmcnt(0)
	v_add_u32_e32 v19, v19, v6
	s_nop 2
	global_load_dword v7, v3, s[4:5] sc1
	v_readlane_b32 s4, v246, 58
	v_readlane_b32 s5, v246, 59
	s_waitcnt vmcnt(0)
	v_add_u32_e32 v19, v19, v7
	s_nop 2
	global_load_dword v8, v3, s[4:5] sc1
	v_readlane_b32 s4, v246, 60
	v_readlane_b32 s5, v246, 61
	s_waitcnt vmcnt(0)
	v_add_u32_e32 v19, v19, v8
	s_nop 2
	global_load_dword v9, v3, s[4:5] sc1
	v_readlane_b32 s4, v246, 62
	v_readlane_b32 s5, v246, 63
	s_waitcnt vmcnt(0)
	v_add_u32_e32 v19, v19, v9
	s_nop 2
	global_load_dword v10, v3, s[4:5] sc1
	v_readlane_b32 s4, v245, 0
	v_readlane_b32 s5, v245, 1
	s_waitcnt vmcnt(0)
	v_add_u32_e32 v19, v19, v10
	s_nop 2
	global_load_dword v11, v3, s[4:5] sc1
	v_readlane_b32 s4, v245, 2
	v_readlane_b32 s5, v245, 3
	s_waitcnt vmcnt(0)
	v_add_u32_e32 v19, v19, v11
	s_nop 2
	global_load_dword v12, v3, s[4:5] sc1
	v_readlane_b32 s4, v245, 4
	v_readlane_b32 s5, v245, 5
	s_waitcnt vmcnt(0)
	v_add_u32_e32 v19, v19, v12
	s_nop 2
	global_load_dword v13, v3, s[4:5] sc1
	v_readlane_b32 s4, v245, 6
	v_readlane_b32 s5, v245, 7
	s_waitcnt vmcnt(0)
	v_add_u32_e32 v19, v19, v13
	s_nop 2
	global_load_dword v14, v3, s[4:5] sc1
	v_readlane_b32 s4, v245, 8
	v_readlane_b32 s5, v245, 9
	s_waitcnt vmcnt(0)
	v_add_u32_e32 v19, v19, v14
	s_nop 2
	global_load_dword v15, v3, s[4:5] sc1
	v_readlane_b32 s4, v245, 10
	v_readlane_b32 s5, v245, 11
	s_waitcnt vmcnt(0)
	v_add_u32_e32 v19, v19, v15
	s_nop 2
	global_load_dword v16, v3, s[4:5] sc1
	v_readlane_b32 s4, v245, 12
	v_readlane_b32 s5, v245, 13
	s_waitcnt vmcnt(0)
	v_add_u32_e32 v19, v19, v16
	s_nop 2
	global_load_dword v17, v3, s[4:5] sc1
	v_readlane_b32 s4, v245, 14
	v_readlane_b32 s5, v245, 15
	s_waitcnt vmcnt(0)
	v_add_u32_e32 v19, v19, v17
	s_nop 2
	global_load_dword v18, v3, s[4:5] sc1
	s_mov_b64 s[4:5], -1
	s_waitcnt vmcnt(0)
	v_add_u32_e32 v19, v19, v18
	v_cmp_eq_u32_e32 vcc, s16, v19
	s_cbranch_vccnz .LBB0_540
	s_and_b32 s4, s17, 0xff
	s_cmp_eq_u32 s4, 0
	s_mov_b64 s[4:5], -1
	s_mov_b64 s[14:15], -1
	s_cbranch_scc1 .LBB0_545
	s_and_b64 vcc, exec, s[14:15]
	s_cbranch_vccz .LBB0_540

; __device__ __forceinline__ unsigned xb_ld(unsigned* p)              { return __hip_atomic_load(p, __ATOMIC_RELAXED, __HIP_MEMORY_SCOPE_AGENT); }
; __device__ __forceinline__ unsigned xb_add(unsigned* p, unsigned v) { return __hip_atomic_fetch_add(p, v, __ATOMIC_RELAXED, __HIP_MEMORY_SCOPE_AGENT); }
; #define XB_SPIN(cond, bar) do { unsigned _sp = 0; while (cond) { __builtin_amdgcn_s_sleep(1); \
;     if ((++_sp & 255u) == 0u) { if (xb_ld(&(bar)[XB_TMO])) break; if (_sp > XB_SPIN_CAP) { atomicAdd(&(bar)[XB_TMO], 1u); break; } } } } while (0)
; __device__ __forceinline__ void xcd_barrier(const XcdBarrier& b) {
;     ...
;             else XB_SPIN(xb_ld(&bar[XB_TOPGEN]) == tg, bar);
;             __builtin_amdgcn_fence(__ATOMIC_ACQUIRE, "agent");
;             xb_add(&bar[XB_XGEN(b.x)], 1u);
;             asm volatile("s_waitcnt vmcnt(0)" ::: "memory");
;         } else {
;             XB_SPIN(xb_ld(&bar[XB_XGEN(b.x)]) == gen, bar);
.LBB0_557:
	s_and_b32 s20, s25, 0xff
	s_mov_b64 s[18:19], -1
	s_cmp_lg_u32 s20, 0
	s_mov_b64 s[22:23], -1
	s_cbranch_scc0 .LBB0_560
	s_and_b64 vcc, exec, s[22:23]
	s_cbranch_vccz .LBB0_556

; __device__ __forceinline__ unsigned xb_ld(unsigned* p)              { return __hip_atomic_load(p, __ATOMIC_RELAXED, __HIP_MEMORY_SCOPE_AGENT); }
; __device__ __forceinline__ unsigned xb_add(unsigned* p, unsigned v) { return __hip_atomic_fetch_add(p, v, __ATOMIC_RELAXED, __HIP_MEMORY_SCOPE_AGENT); }
; #define XB_SPIN(cond, bar) do { unsigned _sp = 0; while (cond) { __builtin_amdgcn_s_sleep(1); \
;     if ((++_sp & 255u) == 0u) { if (xb_ld(&(bar)[XB_TMO])) break; if (_sp > XB_SPIN_CAP) { atomicAdd(&(bar)[XB_TMO], 1u); break; } } } } while (0)
; __device__ __forceinline__ void xcd_barrier(const XcdBarrier& b) {
;     ...
;             else XB_SPIN(xb_ld(&bar[XB_TOPGEN]) == tg, bar);
;             __builtin_amdgcn_fence(__ATOMIC_ACQUIRE, "agent");
;             xb_add(&bar[XB_XGEN(b.x)], 1u);
;             asm volatile("s_waitcnt vmcnt(0)" ::: "memory");
;         } else {
;             XB_SPIN(xb_ld(&bar[XB_XGEN(b.x)]) == gen, bar);
.LBB0_2332:
	s_and_b32 s20, s24, 0xff
	s_mov_b64 s[18:19], -1
	s_cmp_lg_u32 s20, 0
	s_mov_b64 s[22:23], -1
	s_cbranch_scc0 .LBB0_2335
	s_and_b64 vcc, exec, s[22:23]
	s_cbranch_vccz .LBB0_2331
